# v28: v23 + cross-attention output epilogue as 16 dwordx2 stores per lane (quad transpose, was 64 short stores) and no store drain at its unit barrier
# baseline (speedup 1.0000x reference)
; DI bf16 f2bf(float f) { return (bf16)(pkbf(f, f) & 0xffffu); }
; DI int crow(int r, int hi) { return (r & 3) + 8 * (r >> 2) + 4 * hi; }
;     ...
;     if (active) {
;         if (hi == 0) li_l[r32] = l_reg;
;         asm volatile("s_waitcnt lgkmcnt(0)" ::: "memory");
;         int le = lane; asm volatile("" : "+v"(le));
;         const int r32e = le & 31, hie = le >> 5;
;         bf16* Owl = Ow + r32e;
; #pragma unroll
;         for (int r = 0; r < 16; ++r) { const int orow = crow(r, hie); const float rl = __builtin_amdgcn_rcpf(li_l[orow]); bf16* orp = Owl + (size_t)orow * ldo;
; #pragma unroll
;             for (int d0 = 0; d0 < 4; ++d0) orp[d0 * 32] = f2bf(o[d0][r] * rl); }
;     }
.LBB0_2600:
	s_or_b64 exec, exec, s[0:1]
	s_ashr_i32 s37, s36, 31
	s_lshl_b64 s[0:1], s[36:37], 10
	s_add_u32 s0, s8, s0
	s_addc_u32 s1, s9, s1
	s_add_u32 s0, s0, s53
	s_addc_u32 s1, s1, 0
	v_lshrrev_b32_e32 v131, 5, v159
	v_lshl_add_u32 v130, v131, 4, s52
	v_lshlrev_b32_e32 v129, 12, v131
	v_and_b32_e32 v131, 3, v159
	v_lshl_or_b32 v129, v131, 6, v129
	v_bfe_u32 v131, v159, 2, 3
	v_lshl_or_b32 v129, v131, 3, v129
	s_waitcnt lgkmcnt(0)
	ds_read_b128 v[82:85], v130
	ds_read_b128 v[86:89], v130 offset:32
	ds_read_b128 v[90:93], v130 offset:64
	ds_read_b128 v[94:97], v130 offset:96
	v_and_b32_e32 v131, 2, v159
	v_cmp_eq_u32_e32 vcc, 0, v131
	v_and_b32_e32 v131, 1, v159
	v_mov_b32_e32 v128, 0x5040100
	v_cmp_eq_u32_e64 s[100:101], 1, v131
	v_mov_b32_e32 v131, 0x3020706
	s_nop 1
	v_cndmask_b32_e64 v128, v128, v131, s[100:101]
	s_waitcnt lgkmcnt(0)
	v_rcp_f32_e32 v82, v82
	v_rcp_f32_e32 v83, v83
	v_rcp_f32_e32 v84, v84
	v_rcp_f32_e32 v85, v85
	v_rcp_f32_e32 v86, v86
	v_rcp_f32_e32 v87, v87
	v_rcp_f32_e32 v88, v88
	v_rcp_f32_e32 v89, v89
	v_rcp_f32_e32 v90, v90
	v_rcp_f32_e32 v91, v91
	v_rcp_f32_e32 v92, v92
	v_rcp_f32_e32 v93, v93
	v_rcp_f32_e32 v94, v94
	v_rcp_f32_e32 v95, v95
	v_rcp_f32_e32 v96, v96
	v_rcp_f32_e32 v97, v97
	v_mul_f32_e32 v98, v66, v82
	v_mul_f32_e32 v99, v50, v82
	v_mul_f32_e32 v100, v34, v82
	v_mul_f32_e32 v101, v18, v82
	v_mul_f32_e32 v112, v67, v83
	v_mul_f32_e32 v113, v51, v83
	v_mul_f32_e32 v114, v35, v83
	v_mul_f32_e32 v115, v19, v83
	v_cvt_pk_bf16_f32 v102, v98, v99
	v_cvt_pk_bf16_f32 v103, v100, v101
	v_cvt_pk_bf16_f32 v116, v112, v113
	v_cvt_pk_bf16_f32 v117, v114, v115
	v_cndmask_b32_e32 v104, v102, v103, vcc
	v_cndmask_b32_e32 v118, v116, v117, vcc
	s_add_u32 s100, s0, 0x0
	s_addc_u32 s101, s1, 0
	v_mov_b32_dpp v105, v104 quad_perm:[2,3,0,1] row_mask:0xf bank_mask:0xf
	v_mov_b32_dpp v119, v118 quad_perm:[2,3,0,1] row_mask:0xf bank_mask:0xf
	v_cndmask_b32_e32 v106, v105, v102, vcc
	v_cndmask_b32_e32 v107, v103, v105, vcc
	v_cndmask_b32_e32 v120, v119, v116, vcc
	v_cndmask_b32_e32 v121, v117, v119, vcc
	v_mov_b32_dpp v108, v106 quad_perm:[1,0,3,2] row_mask:0xf bank_mask:0xf
	v_mov_b32_dpp v109, v107 quad_perm:[1,0,3,2] row_mask:0xf bank_mask:0xf
	v_mov_b32_dpp v122, v120 quad_perm:[1,0,3,2] row_mask:0xf bank_mask:0xf
	v_mov_b32_dpp v123, v121 quad_perm:[1,0,3,2] row_mask:0xf bank_mask:0xf
	v_perm_b32 v110, v108, v106, v128
	v_perm_b32 v111, v109, v107, v128
	v_perm_b32 v124, v122, v120, v128
	v_perm_b32 v125, v123, v121, v128
	global_store_dwordx2 v129, v[110:111], s[100:101]
	s_add_u32 s100, s100, 0x400
	s_addc_u32 s101, s101, 0
	global_store_dwordx2 v129, v[124:125], s[100:101]
	v_mul_f32_e32 v98, v68, v84
	v_mul_f32_e32 v99, v52, v84
	v_mul_f32_e32 v100, v36, v84
	v_mul_f32_e32 v101, v20, v84
	v_mul_f32_e32 v112, v69, v85
	v_mul_f32_e32 v113, v53, v85
	v_mul_f32_e32 v114, v37, v85
	v_mul_f32_e32 v115, v21, v85
	v_cvt_pk_bf16_f32 v102, v98, v99
	v_cvt_pk_bf16_f32 v103, v100, v101
	v_cvt_pk_bf16_f32 v116, v112, v113
	v_cvt_pk_bf16_f32 v117, v114, v115
	v_cndmask_b32_e32 v104, v102, v103, vcc
	v_cndmask_b32_e32 v118, v116, v117, vcc
	s_add_u32 s100, s0, 0x800
	s_addc_u32 s101, s1, 0
	v_mov_b32_dpp v105, v104 quad_perm:[2,3,0,1] row_mask:0xf bank_mask:0xf
	v_mov_b32_dpp v119, v118 quad_perm:[2,3,0,1] row_mask:0xf bank_mask:0xf
	v_cndmask_b32_e32 v106, v105, v102, vcc
	v_cndmask_b32_e32 v107, v103, v105, vcc
	v_cndmask_b32_e32 v120, v119, v116, vcc
	v_cndmask_b32_e32 v121, v117, v119, vcc
	v_mov_b32_dpp v108, v106 quad_perm:[1,0,3,2] row_mask:0xf bank_mask:0xf
	v_mov_b32_dpp v109, v107 quad_perm:[1,0,3,2] row_mask:0xf bank_mask:0xf
	v_mov_b32_dpp v122, v120 quad_perm:[1,0,3,2] row_mask:0xf bank_mask:0xf
	v_mov_b32_dpp v123, v121 quad_perm:[1,0,3,2] row_mask:0xf bank_mask:0xf
	v_perm_b32 v110, v108, v106, v128
	v_perm_b32 v111, v109, v107, v128
	v_perm_b32 v124, v122, v120, v128
	v_perm_b32 v125, v123, v121, v128
	global_store_dwordx2 v129, v[110:111], s[100:101]
	s_add_u32 s100, s100, 0x400
	s_addc_u32 s101, s101, 0
	global_store_dwordx2 v129, v[124:125], s[100:101]
	v_mul_f32_e32 v98, v70, v86
	v_mul_f32_e32 v99, v54, v86
	v_mul_f32_e32 v100, v38, v86
	v_mul_f32_e32 v101, v22, v86
	v_mul_f32_e32 v112, v71, v87
	v_mul_f32_e32 v113, v55, v87
	v_mul_f32_e32 v114, v39, v87
	v_mul_f32_e32 v115, v23, v87
	v_cvt_pk_bf16_f32 v102, v98, v99
	v_cvt_pk_bf16_f32 v103, v100, v101
	v_cvt_pk_bf16_f32 v116, v112, v113
	v_cvt_pk_bf16_f32 v117, v114, v115
	v_cndmask_b32_e32 v104, v102, v103, vcc
	v_cndmask_b32_e32 v118, v116, v117, vcc
	s_add_u32 s100, s0, 0x2000
	s_addc_u32 s101, s1, 0
	v_mov_b32_dpp v105, v104 quad_perm:[2,3,0,1] row_mask:0xf bank_mask:0xf
	v_mov_b32_dpp v119, v118 quad_perm:[2,3,0,1] row_mask:0xf bank_mask:0xf
	v_cndmask_b32_e32 v106, v105, v102, vcc
	v_cndmask_b32_e32 v107, v103, v105, vcc
	v_cndmask_b32_e32 v120, v119, v116, vcc
	v_cndmask_b32_e32 v121, v117, v119, vcc
	v_mov_b32_dpp v108, v106 quad_perm:[1,0,3,2] row_mask:0xf bank_mask:0xf
	v_mov_b32_dpp v109, v107 quad_perm:[1,0,3,2] row_mask:0xf bank_mask:0xf
	v_mov_b32_dpp v122, v120 quad_perm:[1,0,3,2] row_mask:0xf bank_mask:0xf
	v_mov_b32_dpp v123, v121 quad_perm:[1,0,3,2] row_mask:0xf bank_mask:0xf
	v_perm_b32 v110, v108, v106, v128
	v_perm_b32 v111, v109, v107, v128
	v_perm_b32 v124, v122, v120, v128
	v_perm_b32 v125, v123, v121, v128
	global_store_dwordx2 v129, v[110:111], s[100:101]
	s_add_u32 s100, s100, 0x400
	s_addc_u32 s101, s101, 0
	global_store_dwordx2 v129, v[124:125], s[100:101]
	v_mul_f32_e32 v98, v72, v88
	v_mul_f32_e32 v99, v56, v88
	v_mul_f32_e32 v100, v40, v88
	v_mul_f32_e32 v101, v24, v88
	v_mul_f32_e32 v112, v73, v89
	v_mul_f32_e32 v113, v57, v89
; DI bf16 f2bf(float f) { return (bf16)(pkbf(f, f) & 0xffffu); }
; DI int crow(int r, int hi) { return (r & 3) + 8 * (r >> 2) + 4 * hi; }
;     ...
;     if (active) {
;         if (hi == 0) li_l[r32] = l_reg;
;         asm volatile("s_waitcnt lgkmcnt(0)" ::: "memory");
;         int le = lane; asm volatile("" : "+v"(le));
;         const int r32e = le & 31, hie = le >> 5;
;         bf16* Owl = Ow + r32e;
; #pragma unroll
;         for (int r = 0; r < 16; ++r) { const int orow = crow(r, hie); const float rl = __builtin_amdgcn_rcpf(li_l[orow]); bf16* orp = Owl + (size_t)orow * ldo;
; #pragma unroll
;             for (int d0 = 0; d0 < 4; ++d0) orp[d0 * 32] = f2bf(o[d0][r] * rl); }
;     }
	v_mul_f32_e32 v114, v41, v89
	v_mul_f32_e32 v115, v25, v89
	v_cvt_pk_bf16_f32 v102, v98, v99
	v_cvt_pk_bf16_f32 v103, v100, v101
	v_cvt_pk_bf16_f32 v116, v112, v113
	v_cvt_pk_bf16_f32 v117, v114, v115
	v_cndmask_b32_e32 v104, v102, v103, vcc
	v_cndmask_b32_e32 v118, v116, v117, vcc
	s_add_u32 s100, s0, 0x2800
	s_addc_u32 s101, s1, 0
	v_mov_b32_dpp v105, v104 quad_perm:[2,3,0,1] row_mask:0xf bank_mask:0xf
	v_mov_b32_dpp v119, v118 quad_perm:[2,3,0,1] row_mask:0xf bank_mask:0xf
	v_cndmask_b32_e32 v106, v105, v102, vcc
	v_cndmask_b32_e32 v107, v103, v105, vcc
	v_cndmask_b32_e32 v120, v119, v116, vcc
	v_cndmask_b32_e32 v121, v117, v119, vcc
	v_mov_b32_dpp v108, v106 quad_perm:[1,0,3,2] row_mask:0xf bank_mask:0xf
	v_mov_b32_dpp v109, v107 quad_perm:[1,0,3,2] row_mask:0xf bank_mask:0xf
	v_mov_b32_dpp v122, v120 quad_perm:[1,0,3,2] row_mask:0xf bank_mask:0xf
	v_mov_b32_dpp v123, v121 quad_perm:[1,0,3,2] row_mask:0xf bank_mask:0xf
	v_perm_b32 v110, v108, v106, v128
	v_perm_b32 v111, v109, v107, v128
	v_perm_b32 v124, v122, v120, v128
	v_perm_b32 v125, v123, v121, v128
	global_store_dwordx2 v129, v[110:111], s[100:101]
	s_add_u32 s100, s100, 0x400
	s_addc_u32 s101, s101, 0
	global_store_dwordx2 v129, v[124:125], s[100:101]
	v_mul_f32_e32 v98, v74, v90
	v_mul_f32_e32 v99, v58, v90
	v_mul_f32_e32 v100, v42, v90
	v_mul_f32_e32 v101, v26, v90
	v_mul_f32_e32 v112, v75, v91
	v_mul_f32_e32 v113, v59, v91
	v_mul_f32_e32 v114, v43, v91
	v_mul_f32_e32 v115, v27, v91
	v_cvt_pk_bf16_f32 v102, v98, v99
	v_cvt_pk_bf16_f32 v103, v100, v101
	v_cvt_pk_bf16_f32 v116, v112, v113
	v_cvt_pk_bf16_f32 v117, v114, v115
	v_cndmask_b32_e32 v104, v102, v103, vcc
	v_cndmask_b32_e32 v118, v116, v117, vcc
	s_add_u32 s100, s0, 0x4000
	s_addc_u32 s101, s1, 0
	v_mov_b32_dpp v105, v104 quad_perm:[2,3,0,1] row_mask:0xf bank_mask:0xf
	v_mov_b32_dpp v119, v118 quad_perm:[2,3,0,1] row_mask:0xf bank_mask:0xf
	v_cndmask_b32_e32 v106, v105, v102, vcc
	v_cndmask_b32_e32 v107, v103, v105, vcc
	v_cndmask_b32_e32 v120, v119, v116, vcc
	v_cndmask_b32_e32 v121, v117, v119, vcc
	v_mov_b32_dpp v108, v106 quad_perm:[1,0,3,2] row_mask:0xf bank_mask:0xf
	v_mov_b32_dpp v109, v107 quad_perm:[1,0,3,2] row_mask:0xf bank_mask:0xf
	v_mov_b32_dpp v122, v120 quad_perm:[1,0,3,2] row_mask:0xf bank_mask:0xf
	v_mov_b32_dpp v123, v121 quad_perm:[1,0,3,2] row_mask:0xf bank_mask:0xf
	v_perm_b32 v110, v108, v106, v128
	v_perm_b32 v111, v109, v107, v128
	v_perm_b32 v124, v122, v120, v128
	v_perm_b32 v125, v123, v121, v128
	global_store_dwordx2 v129, v[110:111], s[100:101]
	s_add_u32 s100, s100, 0x400
	s_addc_u32 s101, s101, 0
	global_store_dwordx2 v129, v[124:125], s[100:101]
	v_mul_f32_e32 v98, v76, v92
	v_mul_f32_e32 v99, v60, v92
	v_mul_f32_e32 v100, v44, v92
	v_mul_f32_e32 v101, v28, v92
	v_mul_f32_e32 v112, v77, v93
	v_mul_f32_e32 v113, v61, v93
	v_mul_f32_e32 v114, v45, v93
	v_mul_f32_e32 v115, v29, v93
	v_cvt_pk_bf16_f32 v102, v98, v99
	v_cvt_pk_bf16_f32 v103, v100, v101
	v_cvt_pk_bf16_f32 v116, v112, v113
	v_cvt_pk_bf16_f32 v117, v114, v115
	v_cndmask_b32_e32 v104, v102, v103, vcc
	v_cndmask_b32_e32 v118, v116, v117, vcc
	s_add_u32 s100, s0, 0x4800
	s_addc_u32 s101, s1, 0
	v_mov_b32_dpp v105, v104 quad_perm:[2,3,0,1] row_mask:0xf bank_mask:0xf
	v_mov_b32_dpp v119, v118 quad_perm:[2,3,0,1] row_mask:0xf bank_mask:0xf
	v_cndmask_b32_e32 v106, v105, v102, vcc
	v_cndmask_b32_e32 v107, v103, v105, vcc
	v_cndmask_b32_e32 v120, v119, v116, vcc
	v_cndmask_b32_e32 v121, v117, v119, vcc
	v_mov_b32_dpp v108, v106 quad_perm:[1,0,3,2] row_mask:0xf bank_mask:0xf
	v_mov_b32_dpp v109, v107 quad_perm:[1,0,3,2] row_mask:0xf bank_mask:0xf
	v_mov_b32_dpp v122, v120 quad_perm:[1,0,3,2] row_mask:0xf bank_mask:0xf
	v_mov_b32_dpp v123, v121 quad_perm:[1,0,3,2] row_mask:0xf bank_mask:0xf
	v_perm_b32 v110, v108, v106, v128
	v_perm_b32 v111, v109, v107, v128
	v_perm_b32 v124, v122, v120, v128
	v_perm_b32 v125, v123, v121, v128
	global_store_dwordx2 v129, v[110:111], s[100:101]
	s_add_u32 s100, s100, 0x400
	s_addc_u32 s101, s101, 0
	global_store_dwordx2 v129, v[124:125], s[100:101]
	v_mul_f32_e32 v98, v78, v94
	v_mul_f32_e32 v99, v62, v94
	v_mul_f32_e32 v100, v46, v94
	v_mul_f32_e32 v101, v30, v94
	v_mul_f32_e32 v112, v79, v95
	v_mul_f32_e32 v113, v63, v95
	v_mul_f32_e32 v114, v47, v95
	v_mul_f32_e32 v115, v31, v95
	v_cvt_pk_bf16_f32 v102, v98, v99
	v_cvt_pk_bf16_f32 v103, v100, v101
	v_cvt_pk_bf16_f32 v116, v112, v113
	v_cvt_pk_bf16_f32 v117, v114, v115
	v_cndmask_b32_e32 v104, v102, v103, vcc
	v_cndmask_b32_e32 v118, v116, v117, vcc
	s_add_u32 s100, s0, 0x6000
	s_addc_u32 s101, s1, 0
	v_mov_b32_dpp v105, v104 quad_perm:[2,3,0,1] row_mask:0xf bank_mask:0xf
	v_mov_b32_dpp v119, v118 quad_perm:[2,3,0,1] row_mask:0xf bank_mask:0xf
	v_cndmask_b32_e32 v106, v105, v102, vcc
	v_cndmask_b32_e32 v107, v103, v105, vcc
	v_cndmask_b32_e32 v120, v119, v116, vcc
	v_cndmask_b32_e32 v121, v117, v119, vcc
	v_mov_b32_dpp v108, v106 quad_perm:[1,0,3,2] row_mask:0xf bank_mask:0xf
	v_mov_b32_dpp v109, v107 quad_perm:[1,0,3,2] row_mask:0xf bank_mask:0xf
	v_mov_b32_dpp v122, v120 quad_perm:[1,0,3,2] row_mask:0xf bank_mask:0xf
	v_mov_b32_dpp v123, v121 quad_perm:[1,0,3,2] row_mask:0xf bank_mask:0xf
	v_perm_b32 v110, v108, v106, v128
	v_perm_b32 v111, v109, v107, v128
	v_perm_b32 v124, v122, v120, v128
	v_perm_b32 v125, v123, v121, v128
	global_store_dwordx2 v129, v[110:111], s[100:101]
	s_add_u32 s100, s100, 0x400
	s_addc_u32 s101, s101, 0
	global_store_dwordx2 v129, v[124:125], s[100:101]
	v_mul_f32_e32 v98, v80, v96
	v_mul_f32_e32 v99, v64, v96
	v_mul_f32_e32 v100, v48, v96
	v_mul_f32_e32 v101, v32, v96
	v_mul_f32_e32 v112, v81, v97
	v_mul_f32_e32 v113, v65, v97
	v_mul_f32_e32 v114, v49, v97
	v_mul_f32_e32 v115, v33, v97
	v_cvt_pk_bf16_f32 v102, v98, v99
	v_cvt_pk_bf16_f32 v103, v100, v101
	v_cvt_pk_bf16_f32 v116, v112, v113
	v_cvt_pk_bf16_f32 v117, v114, v115
	v_cndmask_b32_e32 v104, v102, v103, vcc
	v_cndmask_b32_e32 v118, v116, v117, vcc
	s_add_u32 s100, s0, 0x6800
	s_addc_u32 s101, s1, 0
	v_mov_b32_dpp v105, v104 quad_perm:[2,3,0,1] row_mask:0xf bank_mask:0xf
	v_mov_b32_dpp v119, v118 quad_perm:[2,3,0,1] row_mask:0xf bank_mask:0xf
	v_cndmask_b32_e32 v106, v105, v102, vcc
	v_cndmask_b32_e32 v107, v103, v105, vcc
	v_cndmask_b32_e32 v120, v119, v116, vcc
	v_cndmask_b32_e32 v121, v117, v119, vcc
	v_mov_b32_dpp v108, v106 quad_perm:[1,0,3,2] row_mask:0xf bank_mask:0xf
	v_mov_b32_dpp v109, v107 quad_perm:[1,0,3,2] row_mask:0xf bank_mask:0xf
	v_mov_b32_dpp v122, v120 quad_perm:[1,0,3,2] row_mask:0xf bank_mask:0xf
	v_mov_b32_dpp v123, v121 quad_perm:[1,0,3,2] row_mask:0xf bank_mask:0xf
	v_perm_b32 v110, v108, v106, v128
	v_perm_b32 v111, v109, v107, v128
	v_perm_b32 v124, v122, v120, v128
	v_perm_b32 v125, v123, v121, v128
	global_store_dwordx2 v129, v[110:111], s[100:101]
	s_add_u32 s100, s100, 0x400
	s_addc_u32 s101, s101, 0
	global_store_dwordx2 v129, v[124:125], s[100:101]
; DI bf16 f2bf(float f) { return (bf16)(pkbf(f, f) & 0xffffu); }
; DI int crow(int r, int hi) { return (r & 3) + 8 * (r >> 2) + 4 * hi; }
;     ...
;     if (active) {
;         if (hi == 0) li_l[r32] = l_reg;
;         asm volatile("s_waitcnt lgkmcnt(0)" ::: "memory");
;         int le = lane; asm volatile("" : "+v"(le));
;         const int r32e = le & 31, hie = le >> 5;
;         bf16* Owl = Ow + r32e;
; #pragma unroll
;         for (int r = 0; r < 16; ++r) { const int orow = crow(r, hie); const float rl = __builtin_amdgcn_rcpf(li_l[orow]); bf16* orp = Owl + (size_t)orow * ldo;
; #pragma unroll
;             for (int d0 = 0; d0 < 4; ++d0) orp[d0 * 32] = f2bf(o[d0][r] * rl); }
;     }
;     __syncthreads();
.LBB0_2601:
	s_waitcnt lgkmcnt(0)
	s_barrier
.LBB0_2602:
	s_load_dword s0, s[90:91], 0x0
	s_waitcnt lgkmcnt(0)
	s_add_i32 s51, s51, s0
	s_cmpk_gt_i32 s51, 0x1ff
	s_cbranch_scc1 .LBB0_2628
